# ff1 GEMM (phase 9) output stores made nontemporal (nt) like the in-proj stores: 268 MB streaming output no longer pollutes L2
# speedup vs baseline: 1.0054x; 1.0054x over previous
; DI u32x4 pk8(const f32x4& a, const f32x4& b) { u32x4 w; w.x = pk2(a[0], a[1]); w.y = pk2(a[2], a[3]); w.z = pk2(b[0], b[1]); w.w = pk2(b[2], b[3]); return w; }
; template <bool NT = false> DI void st_rows16(void* base, unsigned pitch_b, unsigned row0, unsigned col0, int fr, int fq, const u32x4& w0, const u32x4& w1) {
;   u32x4 x;
; #pragma unroll
;   for (int e = 0; e < 4; ++e) x[e] = (unsigned)__builtin_amdgcn_update_dpp(0, (int)w1[e], 0x128  , 0xf, 0xf, false);
;   const bool hi = fr >= 8;
;   u32x4 pa, pb;
; #pragma unroll
;   for (int e = 0; e < 4; ++e) { pa[e] = hi ? x[e] : w0[e]; pb[e] = hi ? w0[e] : x[e]; }
;   const unsigned ra = row0 + (unsigned)(fr & 7), ca = col0 + 8u * fq + (hi ? 32u : 0u), cb = col0 + 8u * fq + (hi ? 0u : 32u);
;   if (NT) { __builtin_nontemporal_store(pa, (u32x4*)((char*)base + (ra * pitch_b + ca * 2u))); __builtin_nontemporal_store(pb, (u32x4*)((char*)base + ((ra + 8u) * pitch_b + cb * 2u))); }
;   else { gst<u32x4>(base, ra * pitch_b + ca * 2u, pa); gst<u32x4>(base, (ra + 8u) * pitch_b + cb * 2u, pb); }
; }
;   DI void operator()(g8::Acc& acc, int pm, int pn, int wr, int wc, int fr, int fq) const {
;     using namespace g8;
; #pragma unroll
;     for (int ai = 0; ai < 2; ++ai)
; #pragma unroll
;       for (int m = 0; m < 4; ++m) {
;         const int row = pm * BM + ai * HALF + wr * 64 + m * 16 + fr; const float rs = rsqrtf(ssq[row] * (1.0f / DM) + RMS_EPS) * sc;
;         u32x4 wv[2];
; #pragma unroll
;         for (int bj = 0; bj < 2; ++bj) {
;           f32x4 o0 = acc[ai][bj][m][0] * rs, o1 = acc[ai][bj][m][1] * rs;
;           if (act) {
; #pragma unroll
;             for (int e = 0; e < 4; ++e) { const float a = fmaxf(o0[e], 0.f), b = fmaxf(o1[e], 0.f); o0[e] = a * a; o1[e] = b * b; } }
;           wv[bj] = pk8(o0, o1);
;         }
;         st_rows16(dst, (unsigned)ld * 2u, (unsigned)(row - fr), (unsigned)(pn * BM + wc * 64), fr, fq, wv[0], wv[1]);
;         __builtin_amdgcn_sched_barrier(0);
;       }
;   }
.LBB0_763:
	s_lshl_b32 s0, s42, 8
	s_add_i32 s0, s0, s14
	v_or_b32_e32 v150, s0, v140
	v_ashrrev_i32_e32 v151, 31, v150
	v_lshl_add_u64 v[150:151], v[150:151], 2, s[16:17]
	global_load_dword v152, v[150:151], off
	v_mov_b32_e32 v153, 0
	v_lshl_or_b32 v150, s1, 8, v145
	v_mov_b32_e32 v154, 0
	v_mov_b32_e32 v155, 0
	v_mov_b32_e32 v156, 0
	v_or_b32_e32 v151, v150, v143
	v_or_b32_e32 v157, s0, v142
	v_or_b32_e32 v150, v150, v144
	v_lshlrev_b32_e32 v151, 1, v151
	v_lshlrev_b32_e32 v157, 13, v157
	v_lshlrev_b32_e32 v150, 1, v150
	s_waitcnt vmcnt(0)
	v_fmamk_f32 v152, v152, 0x3a800000, v149
	v_mul_f32_e32 v158, 0x4b800000, v152
	v_cmp_gt_f32_e32 vcc, s21, v152
	s_nop 1
	v_cndmask_b32_e32 v152, v152, v158, vcc
	v_rsq_f32_e32 v152, v152
	v_add_u32_e32 v158, v151, v157
	v_add3_u32 v157, v150, v157, s11
	v_mul_f32_e32 v159, 0x45800000, v152
	v_cndmask_b32_e32 v152, v152, v159, vcc
	v_pk_mul_f32 v[118:119], v[118:119], v[152:153] op_sel_hi:[1,0]
	v_pk_mul_f32 v[116:117], v[116:117], v[152:153] op_sel_hi:[1,0]
	v_pk_mul_f32 v[114:115], v[114:115], v[152:153] op_sel_hi:[1,0]
	v_pk_mul_f32 v[112:113], v[112:113], v[152:153] op_sel_hi:[1,0]
	v_pk_mul_f32 v[126:127], v[126:127], v[152:153] op_sel_hi:[1,0]
	v_pk_mul_f32 v[124:125], v[124:125], v[152:153] op_sel_hi:[1,0]
	v_pk_mul_f32 v[122:123], v[122:123], v[152:153] op_sel_hi:[1,0]
	v_pk_mul_f32 v[120:121], v[120:121], v[152:153] op_sel_hi:[1,0]
	v_max_f32_e32 v116, 0, v116
	v_max_f32_e32 v112, 0, v112
	v_max_f32_e32 v117, 0, v117
	v_max_f32_e32 v113, 0, v113
	v_max_f32_e32 v118, 0, v118
	v_max_f32_e32 v114, 0, v114
	v_max_f32_e32 v119, 0, v119
	v_max_f32_e32 v115, 0, v115
	v_max_f32_e32 v124, 0, v124
	v_max_f32_e32 v120, 0, v120
	v_max_f32_e32 v125, 0, v125
	v_max_f32_e32 v121, 0, v121
	v_max_f32_e32 v126, 0, v126
	v_max_f32_e32 v122, 0, v122
	v_max_f32_e32 v127, 0, v127
	v_max_f32_e32 v123, 0, v123
	v_pk_mul_f32 v[116:117], v[116:117], v[116:117]
	v_pk_mul_f32 v[112:113], v[112:113], v[112:113]
	v_pk_mul_f32 v[118:119], v[118:119], v[118:119]
	v_pk_mul_f32 v[114:115], v[114:115], v[114:115]
	v_pk_mul_f32 v[124:125], v[124:125], v[124:125]
	v_pk_mul_f32 v[120:121], v[120:121], v[120:121]
	v_pk_mul_f32 v[126:127], v[126:127], v[126:127]
	v_pk_mul_f32 v[122:123], v[122:123], v[122:123]
	v_cvt_pk_bf16_f32 v116, v116, v117
	v_cvt_pk_bf16_f32 v117, v118, v119
	v_cvt_pk_bf16_f32 v112, v112, v113
	v_cvt_pk_bf16_f32 v113, v114, v115
	v_cvt_pk_bf16_f32 v124, v124, v125
	v_cvt_pk_bf16_f32 v125, v126, v127
	v_cvt_pk_bf16_f32 v120, v120, v121
	v_cvt_pk_bf16_f32 v121, v122, v123
	v_mov_b32_dpp v153, v116 row_ror:8 row_mask:0xf bank_mask:0xf
	v_mov_b32_dpp v154, v117 row_ror:8 row_mask:0xf bank_mask:0xf
	v_mov_b32_dpp v155, v112 row_ror:8 row_mask:0xf bank_mask:0xf
	v_mov_b32_dpp v156, v113 row_ror:8 row_mask:0xf bank_mask:0xf
	v_cndmask_b32_e64 v112, v124, v153, s[4:5]
	v_cndmask_b32_e64 v113, v125, v154, s[4:5]
	v_cndmask_b32_e64 v114, v120, v155, s[4:5]
	v_cndmask_b32_e64 v115, v121, v156, s[4:5]
	v_cndmask_b32_e64 v116, v153, v124, s[4:5]
	v_cndmask_b32_e64 v117, v154, v125, s[4:5]
	v_cndmask_b32_e64 v118, v155, v120, s[4:5]
	v_cndmask_b32_e64 v119, v156, v121, s[4:5]
	global_store_dwordx4 v158, v[112:115], s[24:25] nt
	global_store_dwordx4 v157, v[116:119], s[24:25] nt
	s_or_b32 s1, s0, 16
	v_or_b32_e32 v112, s1, v140
	v_ashrrev_i32_e32 v113, 31, v112
	v_lshl_add_u64 v[112:113], v[112:113], 2, s[16:17]
	global_load_dword v112, v[112:113], off
	v_mov_b32_e32 v113, 0
	v_mov_b32_e32 v114, 0
	v_mov_b32_e32 v115, 0
	v_mov_b32_e32 v116, 0
	v_or_b32_e32 v117, s1, v142
	v_lshlrev_b32_e32 v117, 13, v117
	s_waitcnt vmcnt(0)
	v_fmamk_f32 v112, v112, 0x3a800000, v149
	v_mul_f32_e32 v118, 0x4b800000, v112
	v_cmp_gt_f32_e32 vcc, s21, v112
	s_nop 1
	v_cndmask_b32_e32 v112, v112, v118, vcc
	v_rsq_f32_e32 v112, v112
	v_add_u32_e32 v118, v151, v117
	v_add3_u32 v117, v150, v117, s11
	v_mul_f32_e32 v119, 0x45800000, v112
	v_cndmask_b32_e32 v112, v112, v119, vcc
	v_pk_mul_f32 v[102:103], v[102:103], v[112:113] op_sel_hi:[1,0]
	v_pk_mul_f32 v[100:101], v[100:101], v[112:113] op_sel_hi:[1,0]
	v_pk_mul_f32 v[98:99], v[98:99], v[112:113] op_sel_hi:[1,0]
	v_pk_mul_f32 v[96:97], v[96:97], v[112:113] op_sel_hi:[1,0]
	v_pk_mul_f32 v[110:111], v[110:111], v[112:113] op_sel_hi:[1,0]
	v_pk_mul_f32 v[108:109], v[108:109], v[112:113] op_sel_hi:[1,0]
	v_pk_mul_f32 v[106:107], v[106:107], v[112:113] op_sel_hi:[1,0]
	v_pk_mul_f32 v[104:105], v[104:105], v[112:113] op_sel_hi:[1,0]
	v_max_f32_e32 v100, 0, v100
	v_max_f32_e32 v96, 0, v96
	v_max_f32_e32 v101, 0, v101
	v_max_f32_e32 v97, 0, v97
	v_max_f32_e32 v102, 0, v102
	v_max_f32_e32 v98, 0, v98
	v_max_f32_e32 v103, 0, v103
	v_max_f32_e32 v99, 0, v99
	v_max_f32_e32 v108, 0, v108
	v_max_f32_e32 v104, 0, v104
	v_max_f32_e32 v109, 0, v109
	v_max_f32_e32 v105, 0, v105
	v_max_f32_e32 v110, 0, v110
	v_max_f32_e32 v106, 0, v106
	v_max_f32_e32 v111, 0, v111
	v_max_f32_e32 v107, 0, v107
	v_pk_mul_f32 v[100:101], v[100:101], v[100:101]
	v_pk_mul_f32 v[96:97], v[96:97], v[96:97]
	v_pk_mul_f32 v[102:103], v[102:103], v[102:103]
	v_pk_mul_f32 v[98:99], v[98:99], v[98:99]
	v_pk_mul_f32 v[108:109], v[108:109], v[108:109]
	v_pk_mul_f32 v[104:105], v[104:105], v[104:105]
	v_pk_mul_f32 v[110:111], v[110:111], v[110:111]
	v_pk_mul_f32 v[106:107], v[106:107], v[106:107]
	v_cvt_pk_bf16_f32 v100, v100, v101
	v_cvt_pk_bf16_f32 v101, v102, v103
	v_cvt_pk_bf16_f32 v96, v96, v97
	v_cvt_pk_bf16_f32 v97, v98, v99
	v_cvt_pk_bf16_f32 v108, v108, v109
	v_cvt_pk_bf16_f32 v109, v110, v111
	v_cvt_pk_bf16_f32 v104, v104, v105
	v_cvt_pk_bf16_f32 v105, v106, v107
	v_mov_b32_dpp v113, v100 row_ror:8 row_mask:0xf bank_mask:0xf
	v_mov_b32_dpp v114, v101 row_ror:8 row_mask:0xf bank_mask:0xf
	v_mov_b32_dpp v115, v96 row_ror:8 row_mask:0xf bank_mask:0xf
	v_mov_b32_dpp v116, v97 row_ror:8 row_mask:0xf bank_mask:0xf
	v_cndmask_b32_e64 v96, v108, v113, s[4:5]
	v_cndmask_b32_e64 v97, v109, v114, s[4:5]
	v_cndmask_b32_e64 v98, v104, v115, s[4:5]
	v_cndmask_b32_e64 v99, v105, v116, s[4:5]
	v_cndmask_b32_e64 v100, v113, v108, s[4:5]
	v_cndmask_b32_e64 v101, v114, v109, s[4:5]
	v_cndmask_b32_e64 v102, v115, v104, s[4:5]
	v_cndmask_b32_e64 v103, v116, v105, s[4:5]
	global_store_dwordx4 v118, v[96:99], s[24:25] nt
	global_store_dwordx4 v117, v[100:103], s[24:25] nt
	s_or_b32 s1, s0, 32
	v_or_b32_e32 v96, s1, v140
	v_ashrrev_i32_e32 v97, 31, v96
	v_lshl_add_u64 v[96:97], v[96:97], 2, s[16:17]
	global_load_dword v96, v[96:97], off
	v_mov_b32_e32 v97, 0
	v_mov_b32_e32 v98, 0
	v_mov_b32_e32 v99, 0
	v_mov_b32_e32 v100, 0
	v_or_b32_e32 v101, s1, v142
	v_lshlrev_b32_e32 v101, 13, v101
	s_waitcnt vmcnt(0)
; DI u32x4 pk8(const f32x4& a, const f32x4& b) { u32x4 w; w.x = pk2(a[0], a[1]); w.y = pk2(a[2], a[3]); w.z = pk2(b[0], b[1]); w.w = pk2(b[2], b[3]); return w; }
; template <bool NT = false> DI void st_rows16(void* base, unsigned pitch_b, unsigned row0, unsigned col0, int fr, int fq, const u32x4& w0, const u32x4& w1) {
;   u32x4 x;
; #pragma unroll
;   for (int e = 0; e < 4; ++e) x[e] = (unsigned)__builtin_amdgcn_update_dpp(0, (int)w1[e], 0x128  , 0xf, 0xf, false);
;   const bool hi = fr >= 8;
;   u32x4 pa, pb;
; #pragma unroll
;   for (int e = 0; e < 4; ++e) { pa[e] = hi ? x[e] : w0[e]; pb[e] = hi ? w0[e] : x[e]; }
;   const unsigned ra = row0 + (unsigned)(fr & 7), ca = col0 + 8u * fq + (hi ? 32u : 0u), cb = col0 + 8u * fq + (hi ? 0u : 32u);
;   if (NT) { __builtin_nontemporal_store(pa, (u32x4*)((char*)base + (ra * pitch_b + ca * 2u))); __builtin_nontemporal_store(pb, (u32x4*)((char*)base + ((ra + 8u) * pitch_b + cb * 2u))); }
;   else { gst<u32x4>(base, ra * pitch_b + ca * 2u, pa); gst<u32x4>(base, (ra + 8u) * pitch_b + cb * 2u, pb); }
; }
;   DI void operator()(g8::Acc& acc, int pm, int pn, int wr, int wc, int fr, int fq) const {
;     using namespace g8;
; #pragma unroll
;     for (int ai = 0; ai < 2; ++ai)
; #pragma unroll
;       for (int m = 0; m < 4; ++m) {
;         const int row = pm * BM + ai * HALF + wr * 64 + m * 16 + fr; const float rs = rsqrtf(ssq[row] * (1.0f / DM) + RMS_EPS) * sc;
;         u32x4 wv[2];
; #pragma unroll
;         for (int bj = 0; bj < 2; ++bj) {
;           f32x4 o0 = acc[ai][bj][m][0] * rs, o1 = acc[ai][bj][m][1] * rs;
;           if (act) {
; #pragma unroll
;             for (int e = 0; e < 4; ++e) { const float a = fmaxf(o0[e], 0.f), b = fmaxf(o1[e], 0.f); o0[e] = a * a; o1[e] = b * b; } }
;           wv[bj] = pk8(o0, o1);
;         }
;         st_rows16(dst, (unsigned)ld * 2u, (unsigned)(row - fr), (unsigned)(pn * BM + wc * 64), fr, fq, wv[0], wv[1]);
;         __builtin_amdgcn_sched_barrier(0);
;       }
;   }
	v_fmamk_f32 v96, v96, 0x3a800000, v149
	v_mul_f32_e32 v102, 0x4b800000, v96
	v_cmp_gt_f32_e32 vcc, s21, v96
	s_nop 1
	v_cndmask_b32_e32 v96, v96, v102, vcc
	v_rsq_f32_e32 v96, v96
	v_add_u32_e32 v102, v151, v101
	v_add3_u32 v101, v150, v101, s11
	v_mul_f32_e32 v103, 0x45800000, v96
	v_cndmask_b32_e32 v96, v96, v103, vcc
	v_pk_mul_f32 v[86:87], v[86:87], v[96:97] op_sel_hi:[1,0]
	v_pk_mul_f32 v[84:85], v[84:85], v[96:97] op_sel_hi:[1,0]
	v_pk_mul_f32 v[82:83], v[82:83], v[96:97] op_sel_hi:[1,0]
	v_pk_mul_f32 v[80:81], v[80:81], v[96:97] op_sel_hi:[1,0]
	v_pk_mul_f32 v[94:95], v[94:95], v[96:97] op_sel_hi:[1,0]
	v_pk_mul_f32 v[92:93], v[92:93], v[96:97] op_sel_hi:[1,0]
	v_pk_mul_f32 v[90:91], v[90:91], v[96:97] op_sel_hi:[1,0]
	v_pk_mul_f32 v[88:89], v[88:89], v[96:97] op_sel_hi:[1,0]
	v_max_f32_e32 v84, 0, v84
	v_max_f32_e32 v80, 0, v80
	v_max_f32_e32 v85, 0, v85
	v_max_f32_e32 v81, 0, v81
	v_max_f32_e32 v86, 0, v86
	v_max_f32_e32 v82, 0, v82
	v_max_f32_e32 v87, 0, v87
	v_max_f32_e32 v83, 0, v83
	v_max_f32_e32 v92, 0, v92
	v_max_f32_e32 v88, 0, v88
	v_max_f32_e32 v93, 0, v93
	v_max_f32_e32 v89, 0, v89
	v_max_f32_e32 v94, 0, v94
	v_max_f32_e32 v90, 0, v90
	v_max_f32_e32 v95, 0, v95
	v_max_f32_e32 v91, 0, v91
	v_pk_mul_f32 v[84:85], v[84:85], v[84:85]
	v_pk_mul_f32 v[80:81], v[80:81], v[80:81]
	v_pk_mul_f32 v[86:87], v[86:87], v[86:87]
	v_pk_mul_f32 v[82:83], v[82:83], v[82:83]
	v_pk_mul_f32 v[92:93], v[92:93], v[92:93]
	v_pk_mul_f32 v[88:89], v[88:89], v[88:89]
	v_pk_mul_f32 v[94:95], v[94:95], v[94:95]
	v_pk_mul_f32 v[90:91], v[90:91], v[90:91]
	v_cvt_pk_bf16_f32 v84, v84, v85
	v_cvt_pk_bf16_f32 v85, v86, v87
	v_cvt_pk_bf16_f32 v80, v80, v81
	v_cvt_pk_bf16_f32 v81, v82, v83
	v_cvt_pk_bf16_f32 v92, v92, v93
	v_cvt_pk_bf16_f32 v93, v94, v95
	v_cvt_pk_bf16_f32 v88, v88, v89
	v_cvt_pk_bf16_f32 v89, v90, v91
	v_mov_b32_dpp v97, v84 row_ror:8 row_mask:0xf bank_mask:0xf
	v_mov_b32_dpp v98, v85 row_ror:8 row_mask:0xf bank_mask:0xf
	v_mov_b32_dpp v99, v80 row_ror:8 row_mask:0xf bank_mask:0xf
	v_mov_b32_dpp v100, v81 row_ror:8 row_mask:0xf bank_mask:0xf
	v_cndmask_b32_e64 v80, v92, v97, s[4:5]
	v_cndmask_b32_e64 v81, v93, v98, s[4:5]
	v_cndmask_b32_e64 v82, v88, v99, s[4:5]
	v_cndmask_b32_e64 v83, v89, v100, s[4:5]
	v_cndmask_b32_e64 v84, v97, v92, s[4:5]
	v_cndmask_b32_e64 v85, v98, v93, s[4:5]
	v_cndmask_b32_e64 v86, v99, v88, s[4:5]
	v_cndmask_b32_e64 v87, v100, v89, s[4:5]
	global_store_dwordx4 v102, v[80:83], s[24:25] nt
	global_store_dwordx4 v101, v[84:87], s[24:25] nt
	s_or_b32 s1, s0, 48
	v_or_b32_e32 v80, s1, v140
	v_ashrrev_i32_e32 v81, 31, v80
	v_lshl_add_u64 v[80:81], v[80:81], 2, s[16:17]
	global_load_dword v80, v[80:81], off
	v_mov_b32_e32 v81, 0
	v_mov_b32_e32 v82, 0
	v_mov_b32_e32 v83, 0
	v_mov_b32_e32 v84, 0
	v_or_b32_e32 v85, s1, v142
	v_lshlrev_b32_e32 v85, 13, v85
	s_waitcnt vmcnt(0)
	v_fmamk_f32 v80, v80, 0x3a800000, v149
	v_mul_f32_e32 v86, 0x4b800000, v80
	v_cmp_gt_f32_e32 vcc, s21, v80
	s_nop 1
	v_cndmask_b32_e32 v80, v80, v86, vcc
	v_rsq_f32_e32 v80, v80
	v_add_u32_e32 v86, v151, v85
	v_add3_u32 v85, v150, v85, s11
	v_mul_f32_e32 v87, 0x45800000, v80
	v_cndmask_b32_e32 v80, v80, v87, vcc
	v_pk_mul_f32 v[70:71], v[70:71], v[80:81] op_sel_hi:[1,0]
	v_pk_mul_f32 v[68:69], v[68:69], v[80:81] op_sel_hi:[1,0]
	v_pk_mul_f32 v[66:67], v[66:67], v[80:81] op_sel_hi:[1,0]
	v_pk_mul_f32 v[64:65], v[64:65], v[80:81] op_sel_hi:[1,0]
	v_pk_mul_f32 v[78:79], v[78:79], v[80:81] op_sel_hi:[1,0]
	v_pk_mul_f32 v[76:77], v[76:77], v[80:81] op_sel_hi:[1,0]
	v_pk_mul_f32 v[74:75], v[74:75], v[80:81] op_sel_hi:[1,0]
	v_pk_mul_f32 v[72:73], v[72:73], v[80:81] op_sel_hi:[1,0]
	v_max_f32_e32 v68, 0, v68
	v_max_f32_e32 v64, 0, v64
	v_max_f32_e32 v69, 0, v69
	v_max_f32_e32 v65, 0, v65
	v_max_f32_e32 v70, 0, v70
	v_max_f32_e32 v66, 0, v66
	v_max_f32_e32 v71, 0, v71
	v_max_f32_e32 v67, 0, v67
	v_max_f32_e32 v76, 0, v76
	v_max_f32_e32 v72, 0, v72
	v_max_f32_e32 v77, 0, v77
	v_max_f32_e32 v73, 0, v73
	v_max_f32_e32 v78, 0, v78
	v_max_f32_e32 v74, 0, v74
	v_max_f32_e32 v79, 0, v79
	v_max_f32_e32 v75, 0, v75
	v_pk_mul_f32 v[68:69], v[68:69], v[68:69]
	v_pk_mul_f32 v[64:65], v[64:65], v[64:65]
	v_pk_mul_f32 v[70:71], v[70:71], v[70:71]
	v_pk_mul_f32 v[66:67], v[66:67], v[66:67]
	v_pk_mul_f32 v[76:77], v[76:77], v[76:77]
	v_pk_mul_f32 v[72:73], v[72:73], v[72:73]
	v_pk_mul_f32 v[78:79], v[78:79], v[78:79]
	v_pk_mul_f32 v[74:75], v[74:75], v[74:75]
	v_cvt_pk_bf16_f32 v68, v68, v69
	v_cvt_pk_bf16_f32 v69, v70, v71
	v_cvt_pk_bf16_f32 v64, v64, v65
	v_cvt_pk_bf16_f32 v65, v66, v67
	v_cvt_pk_bf16_f32 v76, v76, v77
	v_cvt_pk_bf16_f32 v77, v78, v79
	v_cvt_pk_bf16_f32 v72, v72, v73
	v_cvt_pk_bf16_f32 v73, v74, v75
	v_mov_b32_dpp v81, v68 row_ror:8 row_mask:0xf bank_mask:0xf
	v_mov_b32_dpp v82, v69 row_ror:8 row_mask:0xf bank_mask:0xf
	v_mov_b32_dpp v83, v64 row_ror:8 row_mask:0xf bank_mask:0xf
	v_mov_b32_dpp v84, v65 row_ror:8 row_mask:0xf bank_mask:0xf
	v_cndmask_b32_e64 v64, v76, v81, s[4:5]
	v_cndmask_b32_e64 v65, v77, v82, s[4:5]
	v_cndmask_b32_e64 v66, v72, v83, s[4:5]
	v_cndmask_b32_e64 v67, v73, v84, s[4:5]
	v_cndmask_b32_e64 v68, v81, v76, s[4:5]
	v_cndmask_b32_e64 v69, v82, v77, s[4:5]
	v_cndmask_b32_e64 v70, v83, v72, s[4:5]
	v_cndmask_b32_e64 v71, v84, v73, s[4:5]
	global_store_dwordx4 v86, v[64:67], s[24:25] nt
	global_store_dwordx4 v85, v[68:71], s[24:25] nt
	s_add_i32 s1, s0, 0x80
	v_or_b32_e32 v64, s1, v140
	v_ashrrev_i32_e32 v65, 31, v64
	v_lshl_add_u64 v[64:65], v[64:65], 2, s[16:17]
	global_load_dword v64, v[64:65], off
	v_mov_b32_e32 v65, 0
	v_mov_b32_e32 v66, 0
	v_mov_b32_e32 v67, 0
	v_mov_b32_e32 v68, 0
	v_or_b32_e32 v69, s1, v142
	v_lshlrev_b32_e32 v69, 13, v69
	s_waitcnt vmcnt(0)
; DI u32x4 pk8(const f32x4& a, const f32x4& b) { u32x4 w; w.x = pk2(a[0], a[1]); w.y = pk2(a[2], a[3]); w.z = pk2(b[0], b[1]); w.w = pk2(b[2], b[3]); return w; }
; template <bool NT = false> DI void st_rows16(void* base, unsigned pitch_b, unsigned row0, unsigned col0, int fr, int fq, const u32x4& w0, const u32x4& w1) {
;   u32x4 x;
; #pragma unroll
;   for (int e = 0; e < 4; ++e) x[e] = (unsigned)__builtin_amdgcn_update_dpp(0, (int)w1[e], 0x128  , 0xf, 0xf, false);
;   const bool hi = fr >= 8;
;   u32x4 pa, pb;
; #pragma unroll
;   for (int e = 0; e < 4; ++e) { pa[e] = hi ? x[e] : w0[e]; pb[e] = hi ? w0[e] : x[e]; }
;   const unsigned ra = row0 + (unsigned)(fr & 7), ca = col0 + 8u * fq + (hi ? 32u : 0u), cb = col0 + 8u * fq + (hi ? 0u : 32u);
;   if (NT) { __builtin_nontemporal_store(pa, (u32x4*)((char*)base + (ra * pitch_b + ca * 2u))); __builtin_nontemporal_store(pb, (u32x4*)((char*)base + ((ra + 8u) * pitch_b + cb * 2u))); }
;   else { gst<u32x4>(base, ra * pitch_b + ca * 2u, pa); gst<u32x4>(base, (ra + 8u) * pitch_b + cb * 2u, pb); }
; }
;   DI void operator()(g8::Acc& acc, int pm, int pn, int wr, int wc, int fr, int fq) const {
;     ...
;     for (int ai = 0; ai < 2; ++ai)
; #pragma unroll
;       for (int m = 0; m < 4; ++m) {
;         const int row = pm * BM + ai * HALF + wr * 64 + m * 16 + fr; const float rs = rsqrtf(ssq[row] * (1.0f / DM) + RMS_EPS) * sc;
;         u32x4 wv[2];
; #pragma unroll
;         for (int bj = 0; bj < 2; ++bj) {
;           f32x4 o0 = acc[ai][bj][m][0] * rs, o1 = acc[ai][bj][m][1] * rs;
;           if (act) {
; #pragma unroll
;             for (int e = 0; e < 4; ++e) { const float a = fmaxf(o0[e], 0.f), b = fmaxf(o1[e], 0.f); o0[e] = a * a; o1[e] = b * b; } }
;           wv[bj] = pk8(o0, o1);
;         }
;         st_rows16(dst, (unsigned)ld * 2u, (unsigned)(row - fr), (unsigned)(pn * BM + wc * 64), fr, fq, wv[0], wv[1]);
;         __builtin_amdgcn_sched_barrier(0);
	v_fmamk_f32 v64, v64, 0x3a800000, v149
	v_mul_f32_e32 v70, 0x4b800000, v64
	v_cmp_gt_f32_e32 vcc, s21, v64
	s_nop 1
	v_cndmask_b32_e32 v64, v64, v70, vcc
	v_rsq_f32_e32 v64, v64
	v_add_u32_e32 v70, v151, v69
	v_add3_u32 v69, v150, v69, s11
	v_mul_f32_e32 v71, 0x45800000, v64
	v_cndmask_b32_e32 v64, v64, v71, vcc
	v_pk_mul_f32 v[54:55], v[54:55], v[64:65] op_sel_hi:[1,0]
	v_pk_mul_f32 v[52:53], v[52:53], v[64:65] op_sel_hi:[1,0]
	v_pk_mul_f32 v[50:51], v[50:51], v[64:65] op_sel_hi:[1,0]
	v_pk_mul_f32 v[48:49], v[48:49], v[64:65] op_sel_hi:[1,0]
	v_pk_mul_f32 v[62:63], v[62:63], v[64:65] op_sel_hi:[1,0]
	v_pk_mul_f32 v[60:61], v[60:61], v[64:65] op_sel_hi:[1,0]
	v_pk_mul_f32 v[58:59], v[58:59], v[64:65] op_sel_hi:[1,0]
	v_pk_mul_f32 v[56:57], v[56:57], v[64:65] op_sel_hi:[1,0]
	v_max_f32_e32 v52, 0, v52
	v_max_f32_e32 v48, 0, v48
	v_max_f32_e32 v53, 0, v53
	v_max_f32_e32 v49, 0, v49
	v_max_f32_e32 v54, 0, v54
	v_max_f32_e32 v50, 0, v50
	v_max_f32_e32 v55, 0, v55
	v_max_f32_e32 v51, 0, v51
	v_max_f32_e32 v60, 0, v60
	v_max_f32_e32 v56, 0, v56
	v_max_f32_e32 v61, 0, v61
	v_max_f32_e32 v57, 0, v57
	v_max_f32_e32 v62, 0, v62
	v_max_f32_e32 v58, 0, v58
	v_max_f32_e32 v63, 0, v63
	v_max_f32_e32 v59, 0, v59
	v_pk_mul_f32 v[52:53], v[52:53], v[52:53]
	v_pk_mul_f32 v[48:49], v[48:49], v[48:49]
	v_pk_mul_f32 v[54:55], v[54:55], v[54:55]
	v_pk_mul_f32 v[50:51], v[50:51], v[50:51]
	v_pk_mul_f32 v[60:61], v[60:61], v[60:61]
	v_pk_mul_f32 v[56:57], v[56:57], v[56:57]
	v_pk_mul_f32 v[62:63], v[62:63], v[62:63]
	v_pk_mul_f32 v[58:59], v[58:59], v[58:59]
	v_cvt_pk_bf16_f32 v52, v52, v53
	v_cvt_pk_bf16_f32 v53, v54, v55
	v_cvt_pk_bf16_f32 v48, v48, v49
	v_cvt_pk_bf16_f32 v49, v50, v51
	v_cvt_pk_bf16_f32 v60, v60, v61
	v_cvt_pk_bf16_f32 v61, v62, v63
	v_cvt_pk_bf16_f32 v56, v56, v57
	v_cvt_pk_bf16_f32 v57, v58, v59
	v_mov_b32_dpp v65, v52 row_ror:8 row_mask:0xf bank_mask:0xf
	v_mov_b32_dpp v66, v53 row_ror:8 row_mask:0xf bank_mask:0xf
	v_mov_b32_dpp v67, v48 row_ror:8 row_mask:0xf bank_mask:0xf
	v_mov_b32_dpp v68, v49 row_ror:8 row_mask:0xf bank_mask:0xf
	v_cndmask_b32_e64 v48, v60, v65, s[4:5]
	v_cndmask_b32_e64 v49, v61, v66, s[4:5]
	v_cndmask_b32_e64 v50, v56, v67, s[4:5]
	v_cndmask_b32_e64 v51, v57, v68, s[4:5]
	v_cndmask_b32_e64 v52, v65, v60, s[4:5]
	v_cndmask_b32_e64 v53, v66, v61, s[4:5]
	v_cndmask_b32_e64 v54, v67, v56, s[4:5]
	v_cndmask_b32_e64 v55, v68, v57, s[4:5]
	global_store_dwordx4 v70, v[48:51], s[24:25] nt
	global_store_dwordx4 v69, v[52:55], s[24:25] nt
	s_add_i32 s1, s0, 0x90
	v_or_b32_e32 v48, s1, v140
	v_ashrrev_i32_e32 v49, 31, v48
	v_lshl_add_u64 v[48:49], v[48:49], 2, s[16:17]
	global_load_dword v48, v[48:49], off
	v_mov_b32_e32 v49, 0
	v_mov_b32_e32 v50, 0
	v_mov_b32_e32 v51, 0
	v_mov_b32_e32 v52, 0
	v_or_b32_e32 v53, s1, v142
	v_lshlrev_b32_e32 v53, 13, v53
	s_waitcnt vmcnt(0)
	v_fmamk_f32 v48, v48, 0x3a800000, v149
	v_mul_f32_e32 v54, 0x4b800000, v48
	v_cmp_gt_f32_e32 vcc, s21, v48
	s_nop 1
	v_cndmask_b32_e32 v48, v48, v54, vcc
	v_rsq_f32_e32 v48, v48
	v_add_u32_e32 v54, v151, v53
	v_add3_u32 v53, v150, v53, s11
	v_mul_f32_e32 v55, 0x45800000, v48
	v_cndmask_b32_e32 v48, v48, v55, vcc
	v_pk_mul_f32 v[38:39], v[38:39], v[48:49] op_sel_hi:[1,0]
	v_pk_mul_f32 v[36:37], v[36:37], v[48:49] op_sel_hi:[1,0]
	v_pk_mul_f32 v[34:35], v[34:35], v[48:49] op_sel_hi:[1,0]
	v_pk_mul_f32 v[32:33], v[32:33], v[48:49] op_sel_hi:[1,0]
	v_pk_mul_f32 v[46:47], v[46:47], v[48:49] op_sel_hi:[1,0]
	v_pk_mul_f32 v[44:45], v[44:45], v[48:49] op_sel_hi:[1,0]
	v_pk_mul_f32 v[42:43], v[42:43], v[48:49] op_sel_hi:[1,0]
	v_pk_mul_f32 v[40:41], v[40:41], v[48:49] op_sel_hi:[1,0]
	v_max_f32_e32 v36, 0, v36
	v_max_f32_e32 v32, 0, v32
	v_max_f32_e32 v37, 0, v37
	v_max_f32_e32 v33, 0, v33
	v_max_f32_e32 v38, 0, v38
	v_max_f32_e32 v34, 0, v34
	v_max_f32_e32 v39, 0, v39
	v_max_f32_e32 v35, 0, v35
	v_max_f32_e32 v44, 0, v44
	v_max_f32_e32 v40, 0, v40
	v_max_f32_e32 v45, 0, v45
	v_max_f32_e32 v41, 0, v41
	v_max_f32_e32 v46, 0, v46
	v_max_f32_e32 v42, 0, v42
	v_max_f32_e32 v47, 0, v47
	v_max_f32_e32 v43, 0, v43
	v_pk_mul_f32 v[36:37], v[36:37], v[36:37]
	v_pk_mul_f32 v[32:33], v[32:33], v[32:33]
	v_pk_mul_f32 v[38:39], v[38:39], v[38:39]
	v_pk_mul_f32 v[34:35], v[34:35], v[34:35]
	v_pk_mul_f32 v[44:45], v[44:45], v[44:45]
	v_pk_mul_f32 v[40:41], v[40:41], v[40:41]
	v_pk_mul_f32 v[46:47], v[46:47], v[46:47]
	v_pk_mul_f32 v[42:43], v[42:43], v[42:43]
	v_cvt_pk_bf16_f32 v36, v36, v37
	v_cvt_pk_bf16_f32 v37, v38, v39
	v_cvt_pk_bf16_f32 v32, v32, v33
	v_cvt_pk_bf16_f32 v33, v34, v35
	v_cvt_pk_bf16_f32 v44, v44, v45
	v_cvt_pk_bf16_f32 v45, v46, v47
	v_cvt_pk_bf16_f32 v40, v40, v41
	v_cvt_pk_bf16_f32 v41, v42, v43
	v_mov_b32_dpp v49, v36 row_ror:8 row_mask:0xf bank_mask:0xf
	v_mov_b32_dpp v50, v37 row_ror:8 row_mask:0xf bank_mask:0xf
	v_mov_b32_dpp v51, v32 row_ror:8 row_mask:0xf bank_mask:0xf
	v_mov_b32_dpp v52, v33 row_ror:8 row_mask:0xf bank_mask:0xf
	v_cndmask_b32_e64 v32, v44, v49, s[4:5]
	v_cndmask_b32_e64 v33, v45, v50, s[4:5]
	v_cndmask_b32_e64 v34, v40, v51, s[4:5]
	v_cndmask_b32_e64 v35, v41, v52, s[4:5]
	v_cndmask_b32_e64 v36, v49, v44, s[4:5]
	v_cndmask_b32_e64 v37, v50, v45, s[4:5]
	v_cndmask_b32_e64 v38, v51, v40, s[4:5]
	v_cndmask_b32_e64 v39, v52, v41, s[4:5]
	global_store_dwordx4 v54, v[32:35], s[24:25] nt
	global_store_dwordx4 v53, v[36:39], s[24:25] nt
	s_add_i32 s1, s0, 0xa0
	v_or_b32_e32 v32, s1, v140
	v_ashrrev_i32_e32 v33, 31, v32
	v_lshl_add_u64 v[32:33], v[32:33], 2, s[16:17]
	global_load_dword v32, v[32:33], off
	v_mov_b32_e32 v33, 0
	v_mov_b32_e32 v34, 0
	v_mov_b32_e32 v35, 0
	v_mov_b32_e32 v36, 0
	v_or_b32_e32 v37, s1, v142
	v_lshlrev_b32_e32 v37, 13, v37
	s_waitcnt vmcnt(0)
; DI u32x4 pk8(const f32x4& a, const f32x4& b) { u32x4 w; w.x = pk2(a[0], a[1]); w.y = pk2(a[2], a[3]); w.z = pk2(b[0], b[1]); w.w = pk2(b[2], b[3]); return w; }
; #define BAR __builtin_amdgcn_s_barrier()
; #define BAR do { __builtin_amdgcn_sched_barrier(0); __builtin_amdgcn_s_barrier(); asm volatile("" ::: "memory"); __builtin_amdgcn_sched_barrier(0); } while (0)
; template <bool SP2, bool ALIGN_EPI, bool DUAL, class Epi> DI void gemm_phase2(const bf16_t* A, const bf16_t* Bt, const bf16_t* A2, const bf16_t* Bt2, int M, int N, int K, const Epi& E, lds_t* lds) {
;     ...
;     if (!has_next) break;
;     if (!(DUAL && pass == 0)) { zero_acc(acc); ++ui; }
;     pm = npm; pn = npn; cA = nA; cB = nB; pass = npass;
;     if constexpr (ALIGN_EPI) { if (wr == 1) BAR; }
;   DI void operator()(g8::Acc& acc, int pm, int pn, int wr, int wc, int fr, int fq) const {
;     ...
;     for (int ai = 0; ai < 2; ++ai)
; #pragma unroll
;       for (int m = 0; m < 4; ++m) {
;         const int row = pm * BM + ai * HALF + wr * 64 + m * 16 + fr; const float rs = rsqrtf(ssq[row] * (1.0f / DM) + RMS_EPS) * sc;
;         u32x4 wv[2];
; #pragma unroll
;         for (int bj = 0; bj < 2; ++bj) {
;           f32x4 o0 = acc[ai][bj][m][0] * rs, o1 = acc[ai][bj][m][1] * rs;
;           if (act) {
; #pragma unroll
;             for (int e = 0; e < 4; ++e) { const float a = fmaxf(o0[e], 0.f), b = fmaxf(o1[e], 0.f); o0[e] = a * a; o1[e] = b * b; } }
;           wv[bj] = pk8(o0, o1);
;         }
;         st_rows16(dst, (unsigned)ld * 2u, (unsigned)(row - fr), (unsigned)(pn * BM + wc * 64), fr, fq, wv[0], wv[1]);
;         __builtin_amdgcn_sched_barrier(0);
	v_fmamk_f32 v32, v32, 0x3a800000, v149
	v_mul_f32_e32 v38, 0x4b800000, v32
	v_cmp_gt_f32_e32 vcc, s21, v32
	s_nop 1
	v_cndmask_b32_e32 v32, v32, v38, vcc
	v_rsq_f32_e32 v32, v32
	v_add_u32_e32 v38, v151, v37
	v_add3_u32 v37, v150, v37, s11
	v_mul_f32_e32 v39, 0x45800000, v32
	v_cndmask_b32_e32 v32, v32, v39, vcc
	v_pk_mul_f32 v[22:23], v[22:23], v[32:33] op_sel_hi:[1,0]
	v_pk_mul_f32 v[20:21], v[20:21], v[32:33] op_sel_hi:[1,0]
	v_pk_mul_f32 v[18:19], v[18:19], v[32:33] op_sel_hi:[1,0]
	v_pk_mul_f32 v[16:17], v[16:17], v[32:33] op_sel_hi:[1,0]
	v_pk_mul_f32 v[30:31], v[30:31], v[32:33] op_sel_hi:[1,0]
	v_pk_mul_f32 v[28:29], v[28:29], v[32:33] op_sel_hi:[1,0]
	v_pk_mul_f32 v[26:27], v[26:27], v[32:33] op_sel_hi:[1,0]
	v_pk_mul_f32 v[24:25], v[24:25], v[32:33] op_sel_hi:[1,0]
	v_max_f32_e32 v20, 0, v20
	v_max_f32_e32 v16, 0, v16
	v_max_f32_e32 v21, 0, v21
	v_max_f32_e32 v17, 0, v17
	v_max_f32_e32 v22, 0, v22
	v_max_f32_e32 v18, 0, v18
	v_max_f32_e32 v23, 0, v23
	v_max_f32_e32 v19, 0, v19
	v_max_f32_e32 v28, 0, v28
	v_max_f32_e32 v24, 0, v24
	v_max_f32_e32 v29, 0, v29
	v_max_f32_e32 v25, 0, v25
	v_max_f32_e32 v30, 0, v30
	v_max_f32_e32 v26, 0, v26
	v_max_f32_e32 v31, 0, v31
	v_max_f32_e32 v27, 0, v27
	v_pk_mul_f32 v[20:21], v[20:21], v[20:21]
	v_pk_mul_f32 v[16:17], v[16:17], v[16:17]
	v_pk_mul_f32 v[22:23], v[22:23], v[22:23]
	v_pk_mul_f32 v[18:19], v[18:19], v[18:19]
	v_pk_mul_f32 v[28:29], v[28:29], v[28:29]
	v_pk_mul_f32 v[24:25], v[24:25], v[24:25]
	v_pk_mul_f32 v[30:31], v[30:31], v[30:31]
	v_pk_mul_f32 v[26:27], v[26:27], v[26:27]
	v_cvt_pk_bf16_f32 v20, v20, v21
	v_cvt_pk_bf16_f32 v21, v22, v23
	v_cvt_pk_bf16_f32 v16, v16, v17
	v_cvt_pk_bf16_f32 v17, v18, v19
	v_cvt_pk_bf16_f32 v28, v28, v29
	v_cvt_pk_bf16_f32 v29, v30, v31
	v_cvt_pk_bf16_f32 v24, v24, v25
	v_cvt_pk_bf16_f32 v25, v26, v27
	v_mov_b32_dpp v33, v20 row_ror:8 row_mask:0xf bank_mask:0xf
	v_mov_b32_dpp v34, v21 row_ror:8 row_mask:0xf bank_mask:0xf
	v_mov_b32_dpp v35, v16 row_ror:8 row_mask:0xf bank_mask:0xf
	v_mov_b32_dpp v36, v17 row_ror:8 row_mask:0xf bank_mask:0xf
	v_cndmask_b32_e64 v16, v28, v33, s[4:5]
	v_cndmask_b32_e64 v17, v29, v34, s[4:5]
	v_cndmask_b32_e64 v18, v24, v35, s[4:5]
	v_cndmask_b32_e64 v19, v25, v36, s[4:5]
	v_cndmask_b32_e64 v20, v33, v28, s[4:5]
	v_cndmask_b32_e64 v21, v34, v29, s[4:5]
	v_cndmask_b32_e64 v22, v35, v24, s[4:5]
	v_cndmask_b32_e64 v23, v36, v25, s[4:5]
	global_store_dwordx4 v38, v[16:19], s[24:25] nt
	global_store_dwordx4 v37, v[20:23], s[24:25] nt
	s_addk_i32 s0, 0xb0
	v_or_b32_e32 v16, s0, v140
	v_ashrrev_i32_e32 v17, 31, v16
	v_lshl_add_u64 v[16:17], v[16:17], 2, s[16:17]
	global_load_dword v16, v[16:17], off
	v_mov_b32_e32 v17, 0
	v_mov_b32_e32 v18, 0
	v_mov_b32_e32 v19, 0
	v_mov_b32_e32 v20, 0
	v_or_b32_e32 v21, s0, v142
	v_lshlrev_b32_e32 v21, 13, v21
	s_waitcnt vmcnt(0)
	v_fmamk_f32 v16, v16, 0x3a800000, v149
	v_mul_f32_e32 v22, 0x4b800000, v16
	v_cmp_gt_f32_e32 vcc, s21, v16
	s_nop 1
	v_cndmask_b32_e32 v16, v16, v22, vcc
	v_rsq_f32_e32 v16, v16
	v_add_u32_e32 v22, v151, v21
	v_add3_u32 v21, v150, v21, s11
	v_mul_f32_e32 v23, 0x45800000, v16
	v_cndmask_b32_e32 v16, v16, v23, vcc
	v_pk_mul_f32 v[6:7], v[6:7], v[16:17] op_sel_hi:[1,0]
	v_pk_mul_f32 v[4:5], v[4:5], v[16:17] op_sel_hi:[1,0]
	v_pk_mul_f32 v[2:3], v[2:3], v[16:17] op_sel_hi:[1,0]
	v_pk_mul_f32 v[0:1], v[0:1], v[16:17] op_sel_hi:[1,0]
	v_pk_mul_f32 v[14:15], v[14:15], v[16:17] op_sel_hi:[1,0]
	v_pk_mul_f32 v[12:13], v[12:13], v[16:17] op_sel_hi:[1,0]
	v_pk_mul_f32 v[10:11], v[10:11], v[16:17] op_sel_hi:[1,0]
	v_pk_mul_f32 v[8:9], v[8:9], v[16:17] op_sel_hi:[1,0]
	v_max_f32_e32 v4, 0, v4
	v_max_f32_e32 v0, 0, v0
	v_max_f32_e32 v5, 0, v5
	v_max_f32_e32 v1, 0, v1
	v_max_f32_e32 v6, 0, v6
	v_max_f32_e32 v2, 0, v2
	v_max_f32_e32 v7, 0, v7
	v_max_f32_e32 v3, 0, v3
	v_max_f32_e32 v12, 0, v12
	v_max_f32_e32 v8, 0, v8
	v_max_f32_e32 v13, 0, v13
	v_max_f32_e32 v9, 0, v9
	v_max_f32_e32 v14, 0, v14
	v_max_f32_e32 v10, 0, v10
	v_max_f32_e32 v15, 0, v15
	v_max_f32_e32 v11, 0, v11
	v_pk_mul_f32 v[4:5], v[4:5], v[4:5]
	v_pk_mul_f32 v[0:1], v[0:1], v[0:1]
	v_pk_mul_f32 v[6:7], v[6:7], v[6:7]
	v_pk_mul_f32 v[2:3], v[2:3], v[2:3]
	v_pk_mul_f32 v[12:13], v[12:13], v[12:13]
	v_pk_mul_f32 v[8:9], v[8:9], v[8:9]
	v_pk_mul_f32 v[14:15], v[14:15], v[14:15]
	v_pk_mul_f32 v[10:11], v[10:11], v[10:11]
	v_cvt_pk_bf16_f32 v4, v4, v5
	v_cvt_pk_bf16_f32 v5, v6, v7
	v_cvt_pk_bf16_f32 v0, v0, v1
	v_cvt_pk_bf16_f32 v1, v2, v3
	v_cvt_pk_bf16_f32 v10, v10, v11
	v_cvt_pk_bf16_f32 v8, v8, v9
	v_cvt_pk_bf16_f32 v9, v14, v15
	v_cvt_pk_bf16_f32 v11, v12, v13
	v_mov_b32_dpp v17, v4 row_ror:8 row_mask:0xf bank_mask:0xf
	v_mov_b32_dpp v18, v5 row_ror:8 row_mask:0xf bank_mask:0xf
	v_mov_b32_dpp v19, v0 row_ror:8 row_mask:0xf bank_mask:0xf
	v_mov_b32_dpp v20, v1 row_ror:8 row_mask:0xf bank_mask:0xf
	v_cndmask_b32_e64 v0, v11, v17, s[4:5]
	v_cndmask_b32_e64 v1, v9, v18, s[4:5]
	v_cndmask_b32_e64 v2, v8, v19, s[4:5]
	v_cndmask_b32_e64 v3, v10, v20, s[4:5]
	v_cndmask_b32_e64 v4, v17, v11, s[4:5]
	v_cndmask_b32_e64 v5, v18, v9, s[4:5]
	v_cndmask_b32_e64 v6, v19, v8, s[4:5]
	v_cndmask_b32_e64 v7, v20, v10, s[4:5]
	global_store_dwordx4 v22, v[0:3], s[24:25] nt
	global_store_dwordx4 v21, v[4:7], s[24:25] nt
	s_andn2_b64 vcc, exec, s[36:37]
	s_mov_b64 s[0:1], -1
	s_cbranch_vccnz .LBB0_756
	s_andn2_b64 vcc, exec, s[6:7]
	s_cbranch_vccnz .LBB0_755
	s_barrier
	s_branch .LBB0_755
